# pool mixer: five row loads issued together with one wait; window sums unrolled with 16 LDS reads in flight and exec-masked adds instead of a serialized per-lane-trip-count loop
# baseline (speedup 1.0000x reference)
.LBB0_699:
	s_and_b64 vcc, exec, s[0:1]
	s_cbranch_vccz .LBB0_722
	v_readlane_b32 s0, v254, 62
	v_readlane_b32 s2, v255, 33
	v_readlane_b32 s3, v255, 34
	v_mov_b32_e32 v0, s0
	s_waitcnt vmcnt(0) lgkmcnt(0)
	ds_read_b64 v[2:3], v0
	v_mov_b32_e32 v24, v240
	s_waitcnt lgkmcnt(0)
	v_readfirstlane_b32 s1, v2
	v_readfirstlane_b32 s0, v3
	s_add_u32 s14, s1, s2
	s_addc_u32 s15, s0, s3
	s_add_i32 s2, s13, 0xfffffc00
	s_lshl_b32 s0, s2, 6
	s_and_b32 s1, s0, 0x7c0
	s_sub_i32 s17, 14, s1
	s_add_i32 s18, s0, -15
	v_ashrrev_i32_e32 v17, 5, v24
	s_movk_i32 s0, 0x9e0
	v_cmp_gt_i32_e64 s[0:1], s0, v24
	v_cmp_lt_i32_e32 vcc, s17, v17
	v_lshlrev_b32_e32 v25, 4, v24
	s_and_b64 vcc, s[0:1], vcc
	v_and_b32_e32 v0, 0x1f0, v25
	v_cndmask_b32_e32 v2, 15, v17, vcc
	v_readlane_b32 s100, v255, 41
	v_readlane_b32 s101, v255, 42
	s_nop 1
	v_lshl_add_u64 v[14:15], s[100:101], 0, v[0:1]
	v_add_u32_e32 v2, s18, v2
	v_mad_i64_i32 v[2:3], s[4:5], v2, s76, v[14:15]
	global_load_dwordx4 v[2:5], v[2:3], off
	v_add_u32_e32 v26, 0x200, v24
	v_ashrrev_i32_e32 v94, 5, v26
	s_movk_i32 s4, 0x7e0
	v_cmp_gt_i32_e64 s[4:5], s4, v24
	v_add_u32_e32 v27, 0x400, v24
	v_ashrrev_i32_e32 v95, 5, v27
	v_add_u32_e32 v28, 0x600, v24
	v_ashrrev_i32_e32 v96, 5, v28
	v_add_u32_e32 v29, 0x800, v24
	v_ashrrev_i32_e32 v97, 5, v29
	v_readfirstlane_b32 s16, v24
	v_and_b32_e32 v30, 31, v24
	v_bfe_u32 v31, v24, 5, 1
	v_and_b32_e32 v32, 7, v24
	v_bfe_u32 v33, v24, 1, 2
	v_lshlrev_b32_e32 v32, 6, v32
	v_lshlrev_b32_e32 v26, 4, v26
	v_lshlrev_b32_e32 v27, 4, v27
	v_lshlrev_b32_e32 v28, 4, v28
	v_lshlrev_b32_e32 v29, 4, v29
	v_and_b32_e32 v25, 0xfffffe00, v25
	v_and_b32_e32 v26, 0xfffffe00, v26
	v_and_b32_e32 v27, 0xfffffe00, v27
	v_and_b32_e32 v28, 0xfffffe00, v28
	v_and_b32_e32 v29, 0xfffffe00, v29
	s_mov_b32 s3, 0
	v_cmp_lt_i32_e32 vcc, s17, v94
	s_and_b64 vcc, s[4:5], vcc
	s_nop 0
	v_cndmask_b32_e32 v6, 15, v94, vcc
	v_add_u32_e32 v6, s18, v6
	v_mad_i64_i32 v[6:7], s[6:7], v6, s76, v[14:15]
	global_load_dwordx4 v[6:9], v[6:7], off
	s_movk_i32 s6, 0x5e0
	v_cmp_gt_i32_e64 s[6:7], s6, v24
	v_cmp_lt_i32_e32 vcc, s17, v95
	s_and_b64 vcc, s[6:7], vcc
	s_nop 0
	v_cndmask_b32_e32 v10, 15, v95, vcc
	v_add_u32_e32 v10, s18, v10
	v_mad_i64_i32 v[10:11], s[8:9], v10, s76, v[14:15]
	global_load_dwordx4 v[10:13], v[10:11], off
	s_movk_i32 s8, 0x3e0
	v_cmp_gt_i32_e64 s[8:9], s8, v24
	v_cmp_lt_i32_e32 vcc, s17, v96
	s_and_b64 vcc, s[8:9], vcc
	s_nop 0
	v_cndmask_b32_e32 v18, 15, v96, vcc
	v_add_u32_e32 v18, s18, v18
	v_mad_i64_i32 v[18:19], s[10:11], v18, s76, v[14:15]
	global_load_dwordx4 v[18:21], v[18:19], off
	s_movk_i32 s10, 0x1e0
	v_cmp_gt_i32_e64 s[10:11], s10, v24
	v_cmp_lt_i32_e32 vcc, s17, v97
	s_and_b64 vcc, s[10:11], vcc
	s_mov_b32 s98, s17
	s_ashr_i32 s17, s16, 7
	v_cndmask_b32_e32 v184, 15, v97, vcc
	v_add_u32_e32 v184, s18, v184
	v_mad_i64_i32 v[184:185], s[18:19], v184, s76, v[14:15]
	global_load_dwordx4 v[184:187], v[184:185], off
	v_readlane_b32 s18, v255, 31
	v_readlane_b32 s19, v255, 32
	s_waitcnt vmcnt(0)
	v_cmp_lt_i32_e32 vcc, s98, v17
	s_and_b64 vcc, s[0:1], vcc
	s_nop 1
	v_cndmask_b32_e32 v5, 0, v5, vcc
	v_cndmask_b32_e32 v4, 0, v4, vcc
	v_cndmask_b32_e32 v3, 0, v3, vcc
	v_cndmask_b32_e32 v2, 0, v2, vcc
	v_cmp_lt_i32_e32 vcc, s98, v94
	s_and_b64 vcc, s[4:5], vcc
	s_nop 1
	v_cndmask_b32_e32 v9, 0, v9, vcc
	v_cndmask_b32_e32 v8, 0, v8, vcc
	v_cndmask_b32_e32 v7, 0, v7, vcc
	v_cndmask_b32_e32 v6, 0, v6, vcc
	v_cmp_lt_i32_e32 vcc, s98, v95
	s_and_b64 vcc, s[6:7], vcc
	s_nop 1
	v_cndmask_b32_e32 v13, 0, v13, vcc
	v_cndmask_b32_e32 v12, 0, v12, vcc
	v_cndmask_b32_e32 v11, 0, v11, vcc
	v_cndmask_b32_e32 v10, 0, v10, vcc
	v_cmp_lt_i32_e32 vcc, s98, v96
	s_and_b64 vcc, s[8:9], vcc
	s_nop 1
	v_cndmask_b32_e32 v77, 0, v21, vcc
	v_cndmask_b32_e32 v76, 0, v20, vcc
	v_cndmask_b32_e32 v75, 0, v19, vcc
	v_cndmask_b32_e32 v74, 0, v18, vcc
	v_cmp_lt_i32_e32 vcc, s98, v97
	s_and_b64 vcc, s[10:11], vcc
	s_nop 1
	v_cndmask_b32_e32 v89, 0, v187, vcc
	v_cndmask_b32_e32 v88, 0, v186, vcc
	v_cndmask_b32_e32 v87, 0, v185, vcc
	v_cndmask_b32_e32 v86, 0, v184, vcc
	v_lshlrev_b32_e32 v19, 6, v30
	v_lshlrev_b32_e32 v18, 3, v31
	v_lshl_or_b32 v22, s17, 12, v19
	v_or_b32_e32 v18, v22, v18
	v_ashrrev_i32_e32 v19, 31, v18
	v_lshl_add_u64 v[20:21], v[18:19], 1, s[18:19]
	global_load_dwordx4 v[50:53], v[20:21], off
	v_or_b32_e32 v20, 0x800, v18
	v_ashrrev_i32_e32 v21, 31, v20
	v_ashrrev_i32_e32 v19, 31, v22
	v_or_b32_e32 v22, 0x810, v18
	v_lshl_add_u64 v[20:21], v[20:21], 1, s[18:19]
	v_ashrrev_i32_e32 v23, 31, v22
	global_load_dwordx4 v[54:57], v[20:21], off
	v_lshl_add_u64 v[20:21], v[18:19], 1, s[18:19]
	v_lshl_add_u64 v[22:23], v[22:23], 1, s[18:19]
	global_load_dwordx4 v[58:61], v[20:21], off offset:32
	global_load_dwordx4 v[62:65], v[22:23], off
	global_load_dwordx4 v[66:69], v[20:21], off offset:64
	v_or_b32_e32 v22, 0x820, v18
	v_or_b32_e32 v18, 0x830, v18
	v_ashrrev_i32_e32 v23, 31, v22
	v_ashrrev_i32_e32 v19, 31, v18
	v_lshl_add_u64 v[22:23], v[22:23], 1, s[18:19]
	v_lshl_add_u64 v[18:19], v[18:19], 1, s[18:19]
	global_load_dwordx4 v[70:73], v[22:23], off
	global_load_dwordx4 v[78:81], v[20:21], off offset:96
	global_load_dwordx4 v[82:85], v[18:19], off
	v_lshl_or_b32 v18, s17, 6, v30
	v_ashrrev_i32_e32 v19, 31, v18
	v_lshl_add_u64 v[20:21], v[18:19], 2, s[14:15]
	global_load_dword v98, v[20:21], off
	global_load_dword v99, v[20:21], off offset:128
	v_ashrrev_i32_e32 v21, 3, v24
	s_movk_i32 s18, 0x90
	s_mulk_i32 s17, 0x2400
	v_add_u32_e32 v20, 0, v0
	v_lshlrev_b32_e64 v0, v33, 2
	v_add_u32_e32 v100, 1, v21
	v_lshlrev_b32_e32 v34, 9, v21
	v_mul_u32_u24_e32 v33, 0x2400, v33
	v_mul_lo_u32 v21, v21, s18
	s_add_i32 s14, s17, 0
	v_or_b32_e32 v22, 32, v18
	v_add3_u32 v21, 0, v33, v21
	s_lshr_b32 s15, s16, 1
	v_mov_b32_e32 v33, s14
	v_lshl_add_u64 v[90:91], v[18:19], 1, s[68:69]
	v_or_b32_e32 v18, v34, v32
	v_readlane_b32 s14, v254, 63
	s_and_b32 s15, s15, 32
	v_lshlrev_b32_e32 v24, 6, v24
	v_add_u32_e32 v102, s14, v18
	v_readlane_b32 s14, v255, 0
	v_or_b32_e32 v30, s15, v30
	v_ashrrev_i32_e32 v23, 31, v22
	v_add_u32_e32 v103, s14, v18
	v_readlane_b32 s14, v255, 1
	v_add_u32_e32 v35, 0, v34
	v_and_b32_e32 v24, 64, v24
	v_mad_u32_u24 v30, v30, s18, v33
	v_lshlrev_b32_e32 v33, 4, v31
	v_add_u32_e32 v104, s14, v18
	v_readlane_b32 s14, v255, 2
	v_lshl_or_b32 v101, v31, 2, s15
	v_lshl_add_u64 v[92:93], v[22:23], 1, s[68:69]
	v_add_u32_e32 v105, s14, v18
	v_add_u32_e32 v106, v20, v25
	v_add_u32_e32 v107, v20, v26
	v_add_u32_e32 v108, v20, v27
	v_add_u32_e32 v109, v20, v28
	v_add_u32_e32 v110, v20, v29
	v_add_u32_e32 v111, v30, v33
	v_add_u32_e32 v112, v35, v32
	v_add_u32_e32 v113, v21, v24

.LBB0_707:
	s_or_b64 exec, exec, s[14:15]
	s_add_i32 s14, s3, s2
	s_lshl_b32 s16, s14, 6
	s_add_i32 s3, s3, 1
	s_cmp_ge_u32 s3, s80
	s_waitcnt lgkmcnt(0)
	s_barrier
	s_cbranch_scc1 .LBB0_709
	s_add_i32 s14, s16, 64
	s_and_b32 s14, s14, 0x7c0
	s_sub_i32 s17, 14, s14
	v_cmp_lt_i32_e32 vcc, s17, v17
	s_and_b64 vcc, s[0:1], vcc
	s_or_b32 s18, s16, 49
	s_nop 1
	v_cndmask_b32_e32 v2, 15, v17, vcc
	v_add_u32_e32 v2, s18, v2
	v_mad_i64_i32 v[2:3], s[14:15], v2, s76, v[14:15]
	global_load_dwordx4 v[2:5], v[2:3], off
	v_cmp_lt_i32_e32 vcc, s17, v94
	s_and_b64 vcc, s[4:5], vcc
	s_nop 1
	v_cndmask_b32_e32 v6, 15, v94, vcc
	v_add_u32_e32 v6, s18, v6
	v_mad_i64_i32 v[6:7], s[14:15], v6, s76, v[14:15]
	global_load_dwordx4 v[6:9], v[6:7], off
	v_cmp_lt_i32_e32 vcc, s17, v95
	s_and_b64 vcc, s[6:7], vcc
	s_nop 1
	v_cndmask_b32_e32 v10, 15, v95, vcc
	v_add_u32_e32 v10, s18, v10
	v_mad_i64_i32 v[10:11], s[14:15], v10, s76, v[14:15]
	global_load_dwordx4 v[10:13], v[10:11], off
	v_cmp_lt_i32_e32 vcc, s17, v96
	s_and_b64 vcc, s[8:9], vcc
	s_nop 1
	v_cndmask_b32_e32 v18, 15, v96, vcc
	v_add_u32_e32 v18, s18, v18
	v_mad_i64_i32 v[18:19], s[14:15], v18, s76, v[14:15]
	global_load_dwordx4 v[18:21], v[18:19], off
	v_cmp_lt_i32_e32 vcc, s17, v97
	s_and_b64 vcc, s[10:11], vcc
	s_nop 1
	v_cndmask_b32_e32 v184, 15, v97, vcc
	v_add_u32_e32 v184, s18, v184
	v_mad_i64_i32 v[184:185], s[14:15], v184, s76, v[14:15]
	global_load_dwordx4 v[184:187], v[184:185], off
	s_waitcnt vmcnt(0)
	v_cmp_lt_i32_e32 vcc, s17, v17
	s_and_b64 vcc, s[0:1], vcc
	s_nop 1
	v_cndmask_b32_e32 v5, 0, v5, vcc
	v_cndmask_b32_e32 v4, 0, v4, vcc
	v_cndmask_b32_e32 v3, 0, v3, vcc
	v_cndmask_b32_e32 v2, 0, v2, vcc
	v_cmp_lt_i32_e32 vcc, s17, v94
	s_and_b64 vcc, s[4:5], vcc
	s_nop 1
	v_cndmask_b32_e32 v9, 0, v9, vcc
	v_cndmask_b32_e32 v8, 0, v8, vcc
	v_cndmask_b32_e32 v7, 0, v7, vcc
	v_cndmask_b32_e32 v6, 0, v6, vcc
	v_cmp_lt_i32_e32 vcc, s17, v95
	s_and_b64 vcc, s[6:7], vcc
	s_nop 1
	v_cndmask_b32_e32 v13, 0, v13, vcc
	v_cndmask_b32_e32 v12, 0, v12, vcc
	v_cndmask_b32_e32 v11, 0, v11, vcc
	v_cndmask_b32_e32 v10, 0, v10, vcc
	v_cmp_lt_i32_e32 vcc, s17, v96
	s_and_b64 vcc, s[8:9], vcc
	s_nop 1
	v_cndmask_b32_e32 v77, 0, v21, vcc
	v_cndmask_b32_e32 v76, 0, v20, vcc
	v_cndmask_b32_e32 v75, 0, v19, vcc
	v_cndmask_b32_e32 v74, 0, v18, vcc
	v_cmp_lt_i32_e32 vcc, s17, v97
	s_and_b64 vcc, s[10:11], vcc
	s_nop 1
	v_cndmask_b32_e32 v89, 0, v187, vcc
	v_cndmask_b32_e32 v88, 0, v186, vcc
	v_cndmask_b32_e32 v87, 0, v185, vcc
	v_cndmask_b32_e32 v86, 0, v184, vcc
.LBB0_709:
	v_mov_b32_e32 v20, 0
	s_mov_b64 s[14:15], 0
	v_mov_b32_e32 v18, v102
	v_mov_b32_e32 v19, v0
	v_mov_b32_e32 v21, v20
	v_mov_b32_e32 v26, v20
	v_mov_b32_e32 v27, v20
	v_mov_b32_e32 v24, v20
	v_mov_b32_e32 v25, v20
	v_mov_b32_e32 v22, v20
	v_mov_b32_e32 v23, v20
	s_waitcnt lgkmcnt(0)
	s_mov_b64 s[14:15], exec
	v_add_u32_e32 v220, 0xffffe200, v18
	ds_read_b128 v[136:139], v220 offset:7680
	ds_read_b128 v[140:143], v220 offset:7168
	ds_read_b128 v[144:147], v220 offset:6656
	ds_read_b128 v[148:151], v220 offset:6144
	ds_read_b128 v[152:155], v220 offset:5632
	ds_read_b128 v[156:159], v220 offset:5120
	ds_read_b128 v[160:163], v220 offset:4608
	ds_read_b128 v[164:167], v220 offset:4096
	ds_read_b128 v[184:187], v220 offset:3584
	ds_read_b128 v[188:191], v220 offset:3072
	ds_read_b128 v[192:195], v220 offset:2560
	ds_read_b128 v[196:199], v220 offset:2048
	ds_read_b128 v[200:203], v220 offset:1536
	ds_read_b128 v[204:207], v220 offset:1024
	ds_read_b128 v[208:211], v220 offset:512
	ds_read_b128 v[212:215], v220 offset:0
	v_cmp_lt_u32_e64 s[98:99], 2, v0
	v_cmp_lt_u32_e64 s[100:101], 4, v0
	v_cmp_lt_u32_e64 vcc, 8, v0
	s_waitcnt lgkmcnt(15)
	v_and_b32_e32 v217, 0xffff0000, v136
	v_lshlrev_b32_e32 v216, 16, v136
	v_pk_add_f32 v[26:27], v[26:27], v[216:217]
	v_and_b32_e32 v219, 0xffff0000, v137
	v_lshlrev_b32_e32 v218, 16, v137
	v_pk_add_f32 v[24:25], v[24:25], v[218:219]
	v_and_b32_e32 v217, 0xffff0000, v138
	v_lshlrev_b32_e32 v216, 16, v138
	v_pk_add_f32 v[22:23], v[22:23], v[216:217]
	v_and_b32_e32 v219, 0xffff0000, v139
	v_lshlrev_b32_e32 v218, 16, v139
	v_pk_add_f32 v[20:21], v[20:21], v[218:219]
	s_waitcnt lgkmcnt(14)
	v_and_b32_e32 v217, 0xffff0000, v140
	v_lshlrev_b32_e32 v216, 16, v140
	v_pk_add_f32 v[26:27], v[26:27], v[216:217]
	v_and_b32_e32 v219, 0xffff0000, v141
	v_lshlrev_b32_e32 v218, 16, v141
	v_pk_add_f32 v[24:25], v[24:25], v[218:219]
	v_and_b32_e32 v217, 0xffff0000, v142
	v_lshlrev_b32_e32 v216, 16, v142
	v_pk_add_f32 v[22:23], v[22:23], v[216:217]
	v_and_b32_e32 v219, 0xffff0000, v143
	v_lshlrev_b32_e32 v218, 16, v143
	v_pk_add_f32 v[20:21], v[20:21], v[218:219]
	s_and_b64 exec, s[14:15], s[98:99]
	s_waitcnt lgkmcnt(13)
	v_and_b32_e32 v217, 0xffff0000, v144
	v_lshlrev_b32_e32 v216, 16, v144
	v_pk_add_f32 v[26:27], v[26:27], v[216:217]
	v_and_b32_e32 v219, 0xffff0000, v145
	v_lshlrev_b32_e32 v218, 16, v145
	v_pk_add_f32 v[24:25], v[24:25], v[218:219]
	v_and_b32_e32 v217, 0xffff0000, v146
	v_lshlrev_b32_e32 v216, 16, v146
	v_pk_add_f32 v[22:23], v[22:23], v[216:217]
	v_and_b32_e32 v219, 0xffff0000, v147
	v_lshlrev_b32_e32 v218, 16, v147
	v_pk_add_f32 v[20:21], v[20:21], v[218:219]
	s_waitcnt lgkmcnt(12)
	v_and_b32_e32 v217, 0xffff0000, v148
	v_lshlrev_b32_e32 v216, 16, v148
	v_pk_add_f32 v[26:27], v[26:27], v[216:217]
	v_and_b32_e32 v219, 0xffff0000, v149
	v_lshlrev_b32_e32 v218, 16, v149
	v_pk_add_f32 v[24:25], v[24:25], v[218:219]
	v_and_b32_e32 v217, 0xffff0000, v150
	v_lshlrev_b32_e32 v216, 16, v150
	v_pk_add_f32 v[22:23], v[22:23], v[216:217]
	v_and_b32_e32 v219, 0xffff0000, v151
	v_lshlrev_b32_e32 v218, 16, v151
	v_pk_add_f32 v[20:21], v[20:21], v[218:219]
	s_and_b64 exec, s[14:15], s[100:101]
	s_waitcnt lgkmcnt(11)
	v_and_b32_e32 v217, 0xffff0000, v152
	v_lshlrev_b32_e32 v216, 16, v152
	v_pk_add_f32 v[26:27], v[26:27], v[216:217]
	v_and_b32_e32 v219, 0xffff0000, v153
	v_lshlrev_b32_e32 v218, 16, v153
	v_pk_add_f32 v[24:25], v[24:25], v[218:219]
	v_and_b32_e32 v217, 0xffff0000, v154
	v_lshlrev_b32_e32 v216, 16, v154
	v_pk_add_f32 v[22:23], v[22:23], v[216:217]
	v_and_b32_e32 v219, 0xffff0000, v155
	v_lshlrev_b32_e32 v218, 16, v155
	v_pk_add_f32 v[20:21], v[20:21], v[218:219]
	s_waitcnt lgkmcnt(10)
	v_and_b32_e32 v217, 0xffff0000, v156
	v_lshlrev_b32_e32 v216, 16, v156
	v_pk_add_f32 v[26:27], v[26:27], v[216:217]
	v_and_b32_e32 v219, 0xffff0000, v157
	v_lshlrev_b32_e32 v218, 16, v157
	v_pk_add_f32 v[24:25], v[24:25], v[218:219]
	v_and_b32_e32 v217, 0xffff0000, v158
	v_lshlrev_b32_e32 v216, 16, v158
	v_pk_add_f32 v[22:23], v[22:23], v[216:217]
	v_and_b32_e32 v219, 0xffff0000, v159
	v_lshlrev_b32_e32 v218, 16, v159
	v_pk_add_f32 v[20:21], v[20:21], v[218:219]
	s_waitcnt lgkmcnt(9)
	v_and_b32_e32 v217, 0xffff0000, v160
	v_lshlrev_b32_e32 v216, 16, v160
	v_pk_add_f32 v[26:27], v[26:27], v[216:217]
	v_and_b32_e32 v219, 0xffff0000, v161
	v_lshlrev_b32_e32 v218, 16, v161
	v_pk_add_f32 v[24:25], v[24:25], v[218:219]
	v_and_b32_e32 v217, 0xffff0000, v162
	v_lshlrev_b32_e32 v216, 16, v162
	v_pk_add_f32 v[22:23], v[22:23], v[216:217]
	v_and_b32_e32 v219, 0xffff0000, v163
	v_lshlrev_b32_e32 v218, 16, v163
	v_pk_add_f32 v[20:21], v[20:21], v[218:219]
	s_waitcnt lgkmcnt(8)
	v_and_b32_e32 v217, 0xffff0000, v164
	v_lshlrev_b32_e32 v216, 16, v164
	v_pk_add_f32 v[26:27], v[26:27], v[216:217]
	v_and_b32_e32 v219, 0xffff0000, v165
	v_lshlrev_b32_e32 v218, 16, v165
	v_pk_add_f32 v[24:25], v[24:25], v[218:219]
	v_and_b32_e32 v217, 0xffff0000, v166
	v_lshlrev_b32_e32 v216, 16, v166
	v_pk_add_f32 v[22:23], v[22:23], v[216:217]
	v_and_b32_e32 v219, 0xffff0000, v167
	v_lshlrev_b32_e32 v218, 16, v167
	v_pk_add_f32 v[20:21], v[20:21], v[218:219]
	s_and_b64 exec, s[14:15], vcc
	s_waitcnt lgkmcnt(7)
	v_and_b32_e32 v217, 0xffff0000, v184
	v_lshlrev_b32_e32 v216, 16, v184
	v_pk_add_f32 v[26:27], v[26:27], v[216:217]
	v_and_b32_e32 v219, 0xffff0000, v185
	v_lshlrev_b32_e32 v218, 16, v185
	v_pk_add_f32 v[24:25], v[24:25], v[218:219]
	v_and_b32_e32 v217, 0xffff0000, v186
	v_lshlrev_b32_e32 v216, 16, v186
	v_pk_add_f32 v[22:23], v[22:23], v[216:217]
	v_and_b32_e32 v219, 0xffff0000, v187
	v_lshlrev_b32_e32 v218, 16, v187
	v_pk_add_f32 v[20:21], v[20:21], v[218:219]
	s_waitcnt lgkmcnt(6)
	v_and_b32_e32 v217, 0xffff0000, v188
	v_lshlrev_b32_e32 v216, 16, v188
	v_pk_add_f32 v[26:27], v[26:27], v[216:217]
	v_and_b32_e32 v219, 0xffff0000, v189
	v_lshlrev_b32_e32 v218, 16, v189
	v_pk_add_f32 v[24:25], v[24:25], v[218:219]
	v_and_b32_e32 v217, 0xffff0000, v190
	v_lshlrev_b32_e32 v216, 16, v190
	v_pk_add_f32 v[22:23], v[22:23], v[216:217]
	v_and_b32_e32 v219, 0xffff0000, v191
	v_lshlrev_b32_e32 v218, 16, v191
	v_pk_add_f32 v[20:21], v[20:21], v[218:219]
	s_waitcnt lgkmcnt(5)
	v_and_b32_e32 v217, 0xffff0000, v192
	v_lshlrev_b32_e32 v216, 16, v192
	v_pk_add_f32 v[26:27], v[26:27], v[216:217]
	v_and_b32_e32 v219, 0xffff0000, v193
	v_lshlrev_b32_e32 v218, 16, v193
	v_pk_add_f32 v[24:25], v[24:25], v[218:219]
	v_and_b32_e32 v217, 0xffff0000, v194
	v_lshlrev_b32_e32 v216, 16, v194
	v_pk_add_f32 v[22:23], v[22:23], v[216:217]
	v_and_b32_e32 v219, 0xffff0000, v195
	v_lshlrev_b32_e32 v218, 16, v195
	v_pk_add_f32 v[20:21], v[20:21], v[218:219]
	s_waitcnt lgkmcnt(4)
	v_and_b32_e32 v217, 0xffff0000, v196
	v_lshlrev_b32_e32 v216, 16, v196
	v_pk_add_f32 v[26:27], v[26:27], v[216:217]
	v_and_b32_e32 v219, 0xffff0000, v197
	v_lshlrev_b32_e32 v218, 16, v197
	v_pk_add_f32 v[24:25], v[24:25], v[218:219]
	v_and_b32_e32 v217, 0xffff0000, v198
	v_lshlrev_b32_e32 v216, 16, v198
	v_pk_add_f32 v[22:23], v[22:23], v[216:217]
	v_and_b32_e32 v219, 0xffff0000, v199
	v_lshlrev_b32_e32 v218, 16, v199
	v_pk_add_f32 v[20:21], v[20:21], v[218:219]
	s_waitcnt lgkmcnt(3)
	v_and_b32_e32 v217, 0xffff0000, v200
	v_lshlrev_b32_e32 v216, 16, v200
	v_pk_add_f32 v[26:27], v[26:27], v[216:217]
	v_and_b32_e32 v219, 0xffff0000, v201
	v_lshlrev_b32_e32 v218, 16, v201
	v_pk_add_f32 v[24:25], v[24:25], v[218:219]
	v_and_b32_e32 v217, 0xffff0000, v202
	v_lshlrev_b32_e32 v216, 16, v202
	v_pk_add_f32 v[22:23], v[22:23], v[216:217]
	v_and_b32_e32 v219, 0xffff0000, v203
	v_lshlrev_b32_e32 v218, 16, v203
	v_pk_add_f32 v[20:21], v[20:21], v[218:219]
	s_waitcnt lgkmcnt(2)
	v_and_b32_e32 v217, 0xffff0000, v204
	v_lshlrev_b32_e32 v216, 16, v204
	v_pk_add_f32 v[26:27], v[26:27], v[216:217]
	v_and_b32_e32 v219, 0xffff0000, v205
	v_lshlrev_b32_e32 v218, 16, v205
	v_pk_add_f32 v[24:25], v[24:25], v[218:219]
	v_and_b32_e32 v217, 0xffff0000, v206
	v_lshlrev_b32_e32 v216, 16, v206
	v_pk_add_f32 v[22:23], v[22:23], v[216:217]
	v_and_b32_e32 v219, 0xffff0000, v207
	v_lshlrev_b32_e32 v218, 16, v207
	v_pk_add_f32 v[20:21], v[20:21], v[218:219]
	s_waitcnt lgkmcnt(1)
	v_and_b32_e32 v217, 0xffff0000, v208
	v_lshlrev_b32_e32 v216, 16, v208
	v_pk_add_f32 v[26:27], v[26:27], v[216:217]
	v_and_b32_e32 v219, 0xffff0000, v209
	v_lshlrev_b32_e32 v218, 16, v209
	v_pk_add_f32 v[24:25], v[24:25], v[218:219]
	v_and_b32_e32 v217, 0xffff0000, v210
	v_lshlrev_b32_e32 v216, 16, v210
	v_pk_add_f32 v[22:23], v[22:23], v[216:217]
	v_and_b32_e32 v219, 0xffff0000, v211
	v_lshlrev_b32_e32 v218, 16, v211
	v_pk_add_f32 v[20:21], v[20:21], v[218:219]
	s_waitcnt lgkmcnt(0)
	v_and_b32_e32 v217, 0xffff0000, v212
	v_lshlrev_b32_e32 v216, 16, v212
	v_pk_add_f32 v[26:27], v[26:27], v[216:217]
	v_and_b32_e32 v219, 0xffff0000, v213
	v_lshlrev_b32_e32 v218, 16, v213
	v_pk_add_f32 v[24:25], v[24:25], v[218:219]
	v_and_b32_e32 v217, 0xffff0000, v214
	v_lshlrev_b32_e32 v216, 16, v214
	v_pk_add_f32 v[22:23], v[22:23], v[216:217]
	v_and_b32_e32 v219, 0xffff0000, v215
	v_lshlrev_b32_e32 v218, 16, v215
	v_pk_add_f32 v[20:21], v[20:21], v[218:219]
	s_mov_b64 exec, s[14:15]
	s_and_b32 s14, s16, 0x7c0
	v_add_u32_e32 v18, s14, v100
	v_min_i32_e32 v18, v18, v0
	v_cvt_f32_i32_e32 v18, v18
	v_div_scale_f32 v19, s[14:15], v18, v18, 1.0
	v_rcp_f32_e32 v28, v19
	s_mov_b64 s[14:15], 0
	v_fma_f32 v29, -v19, v28, 1.0
	v_fmac_f32_e32 v28, v29, v28
	v_div_scale_f32 v29, vcc, 1.0, v18, 1.0
	v_mul_f32_e32 v30, v29, v28
	v_fma_f32 v31, -v19, v30, v29
	v_fmac_f32_e32 v30, v31, v28
	v_fma_f32 v19, -v19, v30, v29
	v_div_fmas_f32 v19, v19, v28, v30
	ds_read_b128 v[28:31], v112 offset:7680
	v_div_fixup_f32 v18, v19, v18, 1.0
	v_mov_b32_e32 v19, v18
	s_waitcnt lgkmcnt(0)
	v_and_b32_e32 v33, 0xffff0000, v28
	v_lshlrev_b32_e32 v32, 16, v28
	v_pk_fma_f32 v[26:27], v[18:19], v[26:27], v[32:33] op_sel_hi:[0,1,1] neg_lo:[0,0,1] neg_hi:[0,0,1]
	v_and_b32_e32 v33, 0xffff0000, v29
	v_lshlrev_b32_e32 v32, 16, v29
	v_pk_fma_f32 v[24:25], v[18:19], v[24:25], v[32:33] op_sel_hi:[0,1,1] neg_lo:[0,0,1] neg_hi:[0,0,1]
	v_cvt_pk_bf16_f32 v26, v26, v27
	v_cvt_pk_bf16_f32 v27, v24, v25
	v_and_b32_e32 v25, 0xffff0000, v30
	v_lshlrev_b32_e32 v24, 16, v30
	v_pk_fma_f32 v[22:23], v[18:19], v[22:23], v[24:25] op_sel_hi:[0,1,1] neg_lo:[0,0,1] neg_hi:[0,0,1]
	v_cvt_pk_bf16_f32 v28, v22, v23
	v_and_b32_e32 v23, 0xffff0000, v31
	v_lshlrev_b32_e32 v22, 16, v31
	v_pk_fma_f32 v[20:21], v[18:19], v[20:21], v[22:23] op_sel_hi:[0,1,1] neg_lo:[0,0,1] neg_hi:[0,0,1]
	v_cvt_pk_bf16_f32 v29, v20, v21
	v_mov_b32_e32 v20, 0
	ds_write_b128 v113, v[26:29] offset:40448
	v_mov_b32_e32 v28, v103
	v_mov_b32_e32 v29, v0
	v_mov_b32_e32 v21, v20
	v_mov_b32_e32 v26, v20
	v_mov_b32_e32 v27, v20
	v_mov_b32_e32 v24, v20
	v_mov_b32_e32 v25, v20
	v_mov_b32_e32 v22, v20
	v_mov_b32_e32 v23, v20
	s_waitcnt lgkmcnt(0)
	s_mov_b64 s[14:15], exec
	v_add_u32_e32 v220, 0xffffe200, v28
	ds_read_b128 v[136:139], v220 offset:7680
	ds_read_b128 v[140:143], v220 offset:7168
	ds_read_b128 v[144:147], v220 offset:6656
	ds_read_b128 v[148:151], v220 offset:6144
	ds_read_b128 v[152:155], v220 offset:5632
	ds_read_b128 v[156:159], v220 offset:5120
	ds_read_b128 v[160:163], v220 offset:4608
	ds_read_b128 v[164:167], v220 offset:4096
	ds_read_b128 v[184:187], v220 offset:3584
	ds_read_b128 v[188:191], v220 offset:3072
	ds_read_b128 v[192:195], v220 offset:2560
	ds_read_b128 v[196:199], v220 offset:2048
	ds_read_b128 v[200:203], v220 offset:1536
	ds_read_b128 v[204:207], v220 offset:1024
	ds_read_b128 v[208:211], v220 offset:512
	ds_read_b128 v[212:215], v220 offset:0
	v_cmp_lt_u32_e64 s[98:99], 2, v0
	v_cmp_lt_u32_e64 s[100:101], 4, v0
	v_cmp_lt_u32_e64 vcc, 8, v0
	s_waitcnt lgkmcnt(15)
	v_and_b32_e32 v217, 0xffff0000, v136
	v_lshlrev_b32_e32 v216, 16, v136
	v_pk_add_f32 v[26:27], v[26:27], v[216:217]
	v_and_b32_e32 v219, 0xffff0000, v137
	v_lshlrev_b32_e32 v218, 16, v137
	v_pk_add_f32 v[24:25], v[24:25], v[218:219]
	v_and_b32_e32 v217, 0xffff0000, v138
	v_lshlrev_b32_e32 v216, 16, v138
	v_pk_add_f32 v[22:23], v[22:23], v[216:217]
	v_and_b32_e32 v219, 0xffff0000, v139
	v_lshlrev_b32_e32 v218, 16, v139
	v_pk_add_f32 v[20:21], v[20:21], v[218:219]
	s_waitcnt lgkmcnt(14)
	v_and_b32_e32 v217, 0xffff0000, v140
	v_lshlrev_b32_e32 v216, 16, v140
	v_pk_add_f32 v[26:27], v[26:27], v[216:217]
	v_and_b32_e32 v219, 0xffff0000, v141
	v_lshlrev_b32_e32 v218, 16, v141
	v_pk_add_f32 v[24:25], v[24:25], v[218:219]
	v_and_b32_e32 v217, 0xffff0000, v142
	v_lshlrev_b32_e32 v216, 16, v142
	v_pk_add_f32 v[22:23], v[22:23], v[216:217]
	v_and_b32_e32 v219, 0xffff0000, v143
	v_lshlrev_b32_e32 v218, 16, v143
	v_pk_add_f32 v[20:21], v[20:21], v[218:219]
	s_and_b64 exec, s[14:15], s[98:99]
	s_waitcnt lgkmcnt(13)
	v_and_b32_e32 v217, 0xffff0000, v144
	v_lshlrev_b32_e32 v216, 16, v144
	v_pk_add_f32 v[26:27], v[26:27], v[216:217]
	v_and_b32_e32 v219, 0xffff0000, v145
	v_lshlrev_b32_e32 v218, 16, v145
	v_pk_add_f32 v[24:25], v[24:25], v[218:219]
	v_and_b32_e32 v217, 0xffff0000, v146
	v_lshlrev_b32_e32 v216, 16, v146
	v_pk_add_f32 v[22:23], v[22:23], v[216:217]
	v_and_b32_e32 v219, 0xffff0000, v147
	v_lshlrev_b32_e32 v218, 16, v147
	v_pk_add_f32 v[20:21], v[20:21], v[218:219]
	s_waitcnt lgkmcnt(12)
	v_and_b32_e32 v217, 0xffff0000, v148
	v_lshlrev_b32_e32 v216, 16, v148
	v_pk_add_f32 v[26:27], v[26:27], v[216:217]
	v_and_b32_e32 v219, 0xffff0000, v149
	v_lshlrev_b32_e32 v218, 16, v149
	v_pk_add_f32 v[24:25], v[24:25], v[218:219]
	v_and_b32_e32 v217, 0xffff0000, v150
	v_lshlrev_b32_e32 v216, 16, v150
	v_pk_add_f32 v[22:23], v[22:23], v[216:217]
	v_and_b32_e32 v219, 0xffff0000, v151
	v_lshlrev_b32_e32 v218, 16, v151
	v_pk_add_f32 v[20:21], v[20:21], v[218:219]
	s_and_b64 exec, s[14:15], s[100:101]
	s_waitcnt lgkmcnt(11)
	v_and_b32_e32 v217, 0xffff0000, v152
	v_lshlrev_b32_e32 v216, 16, v152
	v_pk_add_f32 v[26:27], v[26:27], v[216:217]
	v_and_b32_e32 v219, 0xffff0000, v153
	v_lshlrev_b32_e32 v218, 16, v153
	v_pk_add_f32 v[24:25], v[24:25], v[218:219]
	v_and_b32_e32 v217, 0xffff0000, v154
	v_lshlrev_b32_e32 v216, 16, v154
	v_pk_add_f32 v[22:23], v[22:23], v[216:217]
	v_and_b32_e32 v219, 0xffff0000, v155
	v_lshlrev_b32_e32 v218, 16, v155
	v_pk_add_f32 v[20:21], v[20:21], v[218:219]
	s_waitcnt lgkmcnt(10)
	v_and_b32_e32 v217, 0xffff0000, v156
	v_lshlrev_b32_e32 v216, 16, v156
	v_pk_add_f32 v[26:27], v[26:27], v[216:217]
	v_and_b32_e32 v219, 0xffff0000, v157
	v_lshlrev_b32_e32 v218, 16, v157
	v_pk_add_f32 v[24:25], v[24:25], v[218:219]
	v_and_b32_e32 v217, 0xffff0000, v158
	v_lshlrev_b32_e32 v216, 16, v158
	v_pk_add_f32 v[22:23], v[22:23], v[216:217]
	v_and_b32_e32 v219, 0xffff0000, v159
	v_lshlrev_b32_e32 v218, 16, v159
	v_pk_add_f32 v[20:21], v[20:21], v[218:219]
	s_waitcnt lgkmcnt(9)
	v_and_b32_e32 v217, 0xffff0000, v160
	v_lshlrev_b32_e32 v216, 16, v160
	v_pk_add_f32 v[26:27], v[26:27], v[216:217]
	v_and_b32_e32 v219, 0xffff0000, v161
	v_lshlrev_b32_e32 v218, 16, v161
	v_pk_add_f32 v[24:25], v[24:25], v[218:219]
	v_and_b32_e32 v217, 0xffff0000, v162
	v_lshlrev_b32_e32 v216, 16, v162
	v_pk_add_f32 v[22:23], v[22:23], v[216:217]
	v_and_b32_e32 v219, 0xffff0000, v163
	v_lshlrev_b32_e32 v218, 16, v163
	v_pk_add_f32 v[20:21], v[20:21], v[218:219]
	s_waitcnt lgkmcnt(8)
	v_and_b32_e32 v217, 0xffff0000, v164
	v_lshlrev_b32_e32 v216, 16, v164
	v_pk_add_f32 v[26:27], v[26:27], v[216:217]
	v_and_b32_e32 v219, 0xffff0000, v165
	v_lshlrev_b32_e32 v218, 16, v165
	v_pk_add_f32 v[24:25], v[24:25], v[218:219]
	v_and_b32_e32 v217, 0xffff0000, v166
	v_lshlrev_b32_e32 v216, 16, v166
	v_pk_add_f32 v[22:23], v[22:23], v[216:217]
	v_and_b32_e32 v219, 0xffff0000, v167
	v_lshlrev_b32_e32 v218, 16, v167
	v_pk_add_f32 v[20:21], v[20:21], v[218:219]
	s_and_b64 exec, s[14:15], vcc
	s_waitcnt lgkmcnt(7)
	v_and_b32_e32 v217, 0xffff0000, v184
	v_lshlrev_b32_e32 v216, 16, v184
	v_pk_add_f32 v[26:27], v[26:27], v[216:217]
	v_and_b32_e32 v219, 0xffff0000, v185
	v_lshlrev_b32_e32 v218, 16, v185
	v_pk_add_f32 v[24:25], v[24:25], v[218:219]
	v_and_b32_e32 v217, 0xffff0000, v186
	v_lshlrev_b32_e32 v216, 16, v186
	v_pk_add_f32 v[22:23], v[22:23], v[216:217]
	v_and_b32_e32 v219, 0xffff0000, v187
	v_lshlrev_b32_e32 v218, 16, v187
	v_pk_add_f32 v[20:21], v[20:21], v[218:219]
	s_waitcnt lgkmcnt(6)
	v_and_b32_e32 v217, 0xffff0000, v188
	v_lshlrev_b32_e32 v216, 16, v188
	v_pk_add_f32 v[26:27], v[26:27], v[216:217]
	v_and_b32_e32 v219, 0xffff0000, v189
	v_lshlrev_b32_e32 v218, 16, v189
	v_pk_add_f32 v[24:25], v[24:25], v[218:219]
	v_and_b32_e32 v217, 0xffff0000, v190
	v_lshlrev_b32_e32 v216, 16, v190
	v_pk_add_f32 v[22:23], v[22:23], v[216:217]
	v_and_b32_e32 v219, 0xffff0000, v191
	v_lshlrev_b32_e32 v218, 16, v191
	v_pk_add_f32 v[20:21], v[20:21], v[218:219]
	s_waitcnt lgkmcnt(5)
	v_and_b32_e32 v217, 0xffff0000, v192
	v_lshlrev_b32_e32 v216, 16, v192
	v_pk_add_f32 v[26:27], v[26:27], v[216:217]
	v_and_b32_e32 v219, 0xffff0000, v193
	v_lshlrev_b32_e32 v218, 16, v193
	v_pk_add_f32 v[24:25], v[24:25], v[218:219]
	v_and_b32_e32 v217, 0xffff0000, v194
	v_lshlrev_b32_e32 v216, 16, v194
	v_pk_add_f32 v[22:23], v[22:23], v[216:217]
	v_and_b32_e32 v219, 0xffff0000, v195
	v_lshlrev_b32_e32 v218, 16, v195
	v_pk_add_f32 v[20:21], v[20:21], v[218:219]
	s_waitcnt lgkmcnt(4)
	v_and_b32_e32 v217, 0xffff0000, v196
	v_lshlrev_b32_e32 v216, 16, v196
	v_pk_add_f32 v[26:27], v[26:27], v[216:217]
	v_and_b32_e32 v219, 0xffff0000, v197
	v_lshlrev_b32_e32 v218, 16, v197
	v_pk_add_f32 v[24:25], v[24:25], v[218:219]
	v_and_b32_e32 v217, 0xffff0000, v198
	v_lshlrev_b32_e32 v216, 16, v198
	v_pk_add_f32 v[22:23], v[22:23], v[216:217]
	v_and_b32_e32 v219, 0xffff0000, v199
	v_lshlrev_b32_e32 v218, 16, v199
	v_pk_add_f32 v[20:21], v[20:21], v[218:219]
	s_waitcnt lgkmcnt(3)
	v_and_b32_e32 v217, 0xffff0000, v200
	v_lshlrev_b32_e32 v216, 16, v200
	v_pk_add_f32 v[26:27], v[26:27], v[216:217]
	v_and_b32_e32 v219, 0xffff0000, v201
	v_lshlrev_b32_e32 v218, 16, v201
	v_pk_add_f32 v[24:25], v[24:25], v[218:219]
	v_and_b32_e32 v217, 0xffff0000, v202
	v_lshlrev_b32_e32 v216, 16, v202
	v_pk_add_f32 v[22:23], v[22:23], v[216:217]
	v_and_b32_e32 v219, 0xffff0000, v203
	v_lshlrev_b32_e32 v218, 16, v203
	v_pk_add_f32 v[20:21], v[20:21], v[218:219]
	s_waitcnt lgkmcnt(2)
	v_and_b32_e32 v217, 0xffff0000, v204
	v_lshlrev_b32_e32 v216, 16, v204
	v_pk_add_f32 v[26:27], v[26:27], v[216:217]
	v_and_b32_e32 v219, 0xffff0000, v205
	v_lshlrev_b32_e32 v218, 16, v205
	v_pk_add_f32 v[24:25], v[24:25], v[218:219]
	v_and_b32_e32 v217, 0xffff0000, v206
	v_lshlrev_b32_e32 v216, 16, v206
	v_pk_add_f32 v[22:23], v[22:23], v[216:217]
	v_and_b32_e32 v219, 0xffff0000, v207
	v_lshlrev_b32_e32 v218, 16, v207
	v_pk_add_f32 v[20:21], v[20:21], v[218:219]
	s_waitcnt lgkmcnt(1)
	v_and_b32_e32 v217, 0xffff0000, v208
	v_lshlrev_b32_e32 v216, 16, v208
	v_pk_add_f32 v[26:27], v[26:27], v[216:217]
	v_and_b32_e32 v219, 0xffff0000, v209
	v_lshlrev_b32_e32 v218, 16, v209
	v_pk_add_f32 v[24:25], v[24:25], v[218:219]
	v_and_b32_e32 v217, 0xffff0000, v210
	v_lshlrev_b32_e32 v216, 16, v210
	v_pk_add_f32 v[22:23], v[22:23], v[216:217]
	v_and_b32_e32 v219, 0xffff0000, v211
	v_lshlrev_b32_e32 v218, 16, v211
	v_pk_add_f32 v[20:21], v[20:21], v[218:219]
	s_waitcnt lgkmcnt(0)
	v_and_b32_e32 v217, 0xffff0000, v212
	v_lshlrev_b32_e32 v216, 16, v212
	v_pk_add_f32 v[26:27], v[26:27], v[216:217]
	v_and_b32_e32 v219, 0xffff0000, v213
	v_lshlrev_b32_e32 v218, 16, v213
	v_pk_add_f32 v[24:25], v[24:25], v[218:219]
	v_and_b32_e32 v217, 0xffff0000, v214
	v_lshlrev_b32_e32 v216, 16, v214
	v_pk_add_f32 v[22:23], v[22:23], v[216:217]
	v_and_b32_e32 v219, 0xffff0000, v215
	v_lshlrev_b32_e32 v218, 16, v215
	v_pk_add_f32 v[20:21], v[20:21], v[218:219]
	s_mov_b64 exec, s[14:15]
	ds_read_b128 v[28:31], v112 offset:7696
	s_mov_b64 s[14:15], 0
	s_waitcnt lgkmcnt(0)
	v_and_b32_e32 v33, 0xffff0000, v28
	v_lshlrev_b32_e32 v32, 16, v28
	v_pk_fma_f32 v[26:27], v[18:19], v[26:27], v[32:33] neg_lo:[0,0,1] neg_hi:[0,0,1]
	v_and_b32_e32 v33, 0xffff0000, v29
	v_lshlrev_b32_e32 v32, 16, v29
	v_pk_fma_f32 v[24:25], v[18:19], v[24:25], v[32:33] neg_lo:[0,0,1] neg_hi:[0,0,1]
	v_cvt_pk_bf16_f32 v26, v26, v27
	v_cvt_pk_bf16_f32 v27, v24, v25
	v_and_b32_e32 v25, 0xffff0000, v30
	v_lshlrev_b32_e32 v24, 16, v30
	v_pk_fma_f32 v[22:23], v[18:19], v[22:23], v[24:25] neg_lo:[0,0,1] neg_hi:[0,0,1]
	s_nop 0
	v_cvt_pk_bf16_f32 v28, v22, v23
	v_and_b32_e32 v23, 0xffff0000, v31
	v_lshlrev_b32_e32 v22, 16, v31
	v_pk_fma_f32 v[20:21], v[18:19], v[20:21], v[22:23] neg_lo:[0,0,1] neg_hi:[0,0,1]
	s_nop 0
	v_cvt_pk_bf16_f32 v29, v20, v21
	v_mov_b32_e32 v20, 0
	ds_write_b128 v113, v[26:29] offset:40464
	v_mov_b32_e32 v28, v104
	v_mov_b32_e32 v29, v0
	v_mov_b32_e32 v21, v20
	v_mov_b32_e32 v26, v20
	v_mov_b32_e32 v27, v20
	v_mov_b32_e32 v24, v20
	v_mov_b32_e32 v25, v20
	v_mov_b32_e32 v22, v20
	v_mov_b32_e32 v23, v20
	s_waitcnt lgkmcnt(0)
	s_mov_b64 s[14:15], exec
	v_add_u32_e32 v220, 0xffffe200, v28
	ds_read_b128 v[136:139], v220 offset:7680
	ds_read_b128 v[140:143], v220 offset:7168
	ds_read_b128 v[144:147], v220 offset:6656
	ds_read_b128 v[148:151], v220 offset:6144
	ds_read_b128 v[152:155], v220 offset:5632
	ds_read_b128 v[156:159], v220 offset:5120
	ds_read_b128 v[160:163], v220 offset:4608
	ds_read_b128 v[164:167], v220 offset:4096
	ds_read_b128 v[184:187], v220 offset:3584
	ds_read_b128 v[188:191], v220 offset:3072
	ds_read_b128 v[192:195], v220 offset:2560
	ds_read_b128 v[196:199], v220 offset:2048
	ds_read_b128 v[200:203], v220 offset:1536
	ds_read_b128 v[204:207], v220 offset:1024
	ds_read_b128 v[208:211], v220 offset:512
	ds_read_b128 v[212:215], v220 offset:0
	v_cmp_lt_u32_e64 s[98:99], 2, v0
	v_cmp_lt_u32_e64 s[100:101], 4, v0
	v_cmp_lt_u32_e64 vcc, 8, v0
	s_waitcnt lgkmcnt(15)
	v_and_b32_e32 v217, 0xffff0000, v136
	v_lshlrev_b32_e32 v216, 16, v136
	v_pk_add_f32 v[26:27], v[26:27], v[216:217]
	v_and_b32_e32 v219, 0xffff0000, v137
	v_lshlrev_b32_e32 v218, 16, v137
	v_pk_add_f32 v[24:25], v[24:25], v[218:219]
	v_and_b32_e32 v217, 0xffff0000, v138
	v_lshlrev_b32_e32 v216, 16, v138
	v_pk_add_f32 v[22:23], v[22:23], v[216:217]
	v_and_b32_e32 v219, 0xffff0000, v139
	v_lshlrev_b32_e32 v218, 16, v139
	v_pk_add_f32 v[20:21], v[20:21], v[218:219]
	s_waitcnt lgkmcnt(14)
	v_and_b32_e32 v217, 0xffff0000, v140
	v_lshlrev_b32_e32 v216, 16, v140
	v_pk_add_f32 v[26:27], v[26:27], v[216:217]
	v_and_b32_e32 v219, 0xffff0000, v141
	v_lshlrev_b32_e32 v218, 16, v141
	v_pk_add_f32 v[24:25], v[24:25], v[218:219]
	v_and_b32_e32 v217, 0xffff0000, v142
	v_lshlrev_b32_e32 v216, 16, v142
	v_pk_add_f32 v[22:23], v[22:23], v[216:217]
	v_and_b32_e32 v219, 0xffff0000, v143
	v_lshlrev_b32_e32 v218, 16, v143
	v_pk_add_f32 v[20:21], v[20:21], v[218:219]
	s_and_b64 exec, s[14:15], s[98:99]
	s_waitcnt lgkmcnt(13)
	v_and_b32_e32 v217, 0xffff0000, v144
	v_lshlrev_b32_e32 v216, 16, v144
	v_pk_add_f32 v[26:27], v[26:27], v[216:217]
	v_and_b32_e32 v219, 0xffff0000, v145
	v_lshlrev_b32_e32 v218, 16, v145
	v_pk_add_f32 v[24:25], v[24:25], v[218:219]
	v_and_b32_e32 v217, 0xffff0000, v146
	v_lshlrev_b32_e32 v216, 16, v146
	v_pk_add_f32 v[22:23], v[22:23], v[216:217]
	v_and_b32_e32 v219, 0xffff0000, v147
	v_lshlrev_b32_e32 v218, 16, v147
	v_pk_add_f32 v[20:21], v[20:21], v[218:219]
	s_waitcnt lgkmcnt(12)
	v_and_b32_e32 v217, 0xffff0000, v148
	v_lshlrev_b32_e32 v216, 16, v148
	v_pk_add_f32 v[26:27], v[26:27], v[216:217]
	v_and_b32_e32 v219, 0xffff0000, v149
	v_lshlrev_b32_e32 v218, 16, v149
	v_pk_add_f32 v[24:25], v[24:25], v[218:219]
	v_and_b32_e32 v217, 0xffff0000, v150
	v_lshlrev_b32_e32 v216, 16, v150
	v_pk_add_f32 v[22:23], v[22:23], v[216:217]
	v_and_b32_e32 v219, 0xffff0000, v151
	v_lshlrev_b32_e32 v218, 16, v151
	v_pk_add_f32 v[20:21], v[20:21], v[218:219]
	s_and_b64 exec, s[14:15], s[100:101]
	s_waitcnt lgkmcnt(11)
	v_and_b32_e32 v217, 0xffff0000, v152
	v_lshlrev_b32_e32 v216, 16, v152
	v_pk_add_f32 v[26:27], v[26:27], v[216:217]
	v_and_b32_e32 v219, 0xffff0000, v153
	v_lshlrev_b32_e32 v218, 16, v153
	v_pk_add_f32 v[24:25], v[24:25], v[218:219]
	v_and_b32_e32 v217, 0xffff0000, v154
	v_lshlrev_b32_e32 v216, 16, v154
	v_pk_add_f32 v[22:23], v[22:23], v[216:217]
	v_and_b32_e32 v219, 0xffff0000, v155
	v_lshlrev_b32_e32 v218, 16, v155
	v_pk_add_f32 v[20:21], v[20:21], v[218:219]
	s_waitcnt lgkmcnt(10)
	v_and_b32_e32 v217, 0xffff0000, v156
	v_lshlrev_b32_e32 v216, 16, v156
	v_pk_add_f32 v[26:27], v[26:27], v[216:217]
	v_and_b32_e32 v219, 0xffff0000, v157
	v_lshlrev_b32_e32 v218, 16, v157
	v_pk_add_f32 v[24:25], v[24:25], v[218:219]
	v_and_b32_e32 v217, 0xffff0000, v158
	v_lshlrev_b32_e32 v216, 16, v158
	v_pk_add_f32 v[22:23], v[22:23], v[216:217]
	v_and_b32_e32 v219, 0xffff0000, v159
	v_lshlrev_b32_e32 v218, 16, v159
	v_pk_add_f32 v[20:21], v[20:21], v[218:219]
	s_waitcnt lgkmcnt(9)
	v_and_b32_e32 v217, 0xffff0000, v160
	v_lshlrev_b32_e32 v216, 16, v160
	v_pk_add_f32 v[26:27], v[26:27], v[216:217]
	v_and_b32_e32 v219, 0xffff0000, v161
	v_lshlrev_b32_e32 v218, 16, v161
	v_pk_add_f32 v[24:25], v[24:25], v[218:219]
	v_and_b32_e32 v217, 0xffff0000, v162
	v_lshlrev_b32_e32 v216, 16, v162
	v_pk_add_f32 v[22:23], v[22:23], v[216:217]
	v_and_b32_e32 v219, 0xffff0000, v163
	v_lshlrev_b32_e32 v218, 16, v163
	v_pk_add_f32 v[20:21], v[20:21], v[218:219]
	s_waitcnt lgkmcnt(8)
	v_and_b32_e32 v217, 0xffff0000, v164
	v_lshlrev_b32_e32 v216, 16, v164
	v_pk_add_f32 v[26:27], v[26:27], v[216:217]
	v_and_b32_e32 v219, 0xffff0000, v165
	v_lshlrev_b32_e32 v218, 16, v165
	v_pk_add_f32 v[24:25], v[24:25], v[218:219]
	v_and_b32_e32 v217, 0xffff0000, v166
	v_lshlrev_b32_e32 v216, 16, v166
	v_pk_add_f32 v[22:23], v[22:23], v[216:217]
	v_and_b32_e32 v219, 0xffff0000, v167
	v_lshlrev_b32_e32 v218, 16, v167
	v_pk_add_f32 v[20:21], v[20:21], v[218:219]
	s_and_b64 exec, s[14:15], vcc
	s_waitcnt lgkmcnt(7)
	v_and_b32_e32 v217, 0xffff0000, v184
	v_lshlrev_b32_e32 v216, 16, v184
	v_pk_add_f32 v[26:27], v[26:27], v[216:217]
	v_and_b32_e32 v219, 0xffff0000, v185
	v_lshlrev_b32_e32 v218, 16, v185
	v_pk_add_f32 v[24:25], v[24:25], v[218:219]
	v_and_b32_e32 v217, 0xffff0000, v186
	v_lshlrev_b32_e32 v216, 16, v186
	v_pk_add_f32 v[22:23], v[22:23], v[216:217]
	v_and_b32_e32 v219, 0xffff0000, v187
	v_lshlrev_b32_e32 v218, 16, v187
	v_pk_add_f32 v[20:21], v[20:21], v[218:219]
	s_waitcnt lgkmcnt(6)
	v_and_b32_e32 v217, 0xffff0000, v188
	v_lshlrev_b32_e32 v216, 16, v188
	v_pk_add_f32 v[26:27], v[26:27], v[216:217]
	v_and_b32_e32 v219, 0xffff0000, v189
	v_lshlrev_b32_e32 v218, 16, v189
	v_pk_add_f32 v[24:25], v[24:25], v[218:219]
	v_and_b32_e32 v217, 0xffff0000, v190
	v_lshlrev_b32_e32 v216, 16, v190
	v_pk_add_f32 v[22:23], v[22:23], v[216:217]
	v_and_b32_e32 v219, 0xffff0000, v191
	v_lshlrev_b32_e32 v218, 16, v191
	v_pk_add_f32 v[20:21], v[20:21], v[218:219]
	s_waitcnt lgkmcnt(5)
	v_and_b32_e32 v217, 0xffff0000, v192
	v_lshlrev_b32_e32 v216, 16, v192
	v_pk_add_f32 v[26:27], v[26:27], v[216:217]
	v_and_b32_e32 v219, 0xffff0000, v193
	v_lshlrev_b32_e32 v218, 16, v193
	v_pk_add_f32 v[24:25], v[24:25], v[218:219]
	v_and_b32_e32 v217, 0xffff0000, v194
	v_lshlrev_b32_e32 v216, 16, v194
	v_pk_add_f32 v[22:23], v[22:23], v[216:217]
	v_and_b32_e32 v219, 0xffff0000, v195
	v_lshlrev_b32_e32 v218, 16, v195
	v_pk_add_f32 v[20:21], v[20:21], v[218:219]
	s_waitcnt lgkmcnt(4)
	v_and_b32_e32 v217, 0xffff0000, v196
	v_lshlrev_b32_e32 v216, 16, v196
	v_pk_add_f32 v[26:27], v[26:27], v[216:217]
	v_and_b32_e32 v219, 0xffff0000, v197
	v_lshlrev_b32_e32 v218, 16, v197
	v_pk_add_f32 v[24:25], v[24:25], v[218:219]
	v_and_b32_e32 v217, 0xffff0000, v198
	v_lshlrev_b32_e32 v216, 16, v198
	v_pk_add_f32 v[22:23], v[22:23], v[216:217]
	v_and_b32_e32 v219, 0xffff0000, v199
	v_lshlrev_b32_e32 v218, 16, v199
	v_pk_add_f32 v[20:21], v[20:21], v[218:219]
	s_waitcnt lgkmcnt(3)
	v_and_b32_e32 v217, 0xffff0000, v200
	v_lshlrev_b32_e32 v216, 16, v200
	v_pk_add_f32 v[26:27], v[26:27], v[216:217]
	v_and_b32_e32 v219, 0xffff0000, v201
	v_lshlrev_b32_e32 v218, 16, v201
	v_pk_add_f32 v[24:25], v[24:25], v[218:219]
	v_and_b32_e32 v217, 0xffff0000, v202
	v_lshlrev_b32_e32 v216, 16, v202
	v_pk_add_f32 v[22:23], v[22:23], v[216:217]
	v_and_b32_e32 v219, 0xffff0000, v203
	v_lshlrev_b32_e32 v218, 16, v203
	v_pk_add_f32 v[20:21], v[20:21], v[218:219]
	s_waitcnt lgkmcnt(2)
	v_and_b32_e32 v217, 0xffff0000, v204
	v_lshlrev_b32_e32 v216, 16, v204
	v_pk_add_f32 v[26:27], v[26:27], v[216:217]
	v_and_b32_e32 v219, 0xffff0000, v205
	v_lshlrev_b32_e32 v218, 16, v205
	v_pk_add_f32 v[24:25], v[24:25], v[218:219]
	v_and_b32_e32 v217, 0xffff0000, v206
	v_lshlrev_b32_e32 v216, 16, v206
	v_pk_add_f32 v[22:23], v[22:23], v[216:217]
	v_and_b32_e32 v219, 0xffff0000, v207
	v_lshlrev_b32_e32 v218, 16, v207
	v_pk_add_f32 v[20:21], v[20:21], v[218:219]
	s_waitcnt lgkmcnt(1)
	v_and_b32_e32 v217, 0xffff0000, v208
	v_lshlrev_b32_e32 v216, 16, v208
	v_pk_add_f32 v[26:27], v[26:27], v[216:217]
	v_and_b32_e32 v219, 0xffff0000, v209
	v_lshlrev_b32_e32 v218, 16, v209
	v_pk_add_f32 v[24:25], v[24:25], v[218:219]
	v_and_b32_e32 v217, 0xffff0000, v210
	v_lshlrev_b32_e32 v216, 16, v210
	v_pk_add_f32 v[22:23], v[22:23], v[216:217]
	v_and_b32_e32 v219, 0xffff0000, v211
	v_lshlrev_b32_e32 v218, 16, v211
	v_pk_add_f32 v[20:21], v[20:21], v[218:219]
	s_waitcnt lgkmcnt(0)
	v_and_b32_e32 v217, 0xffff0000, v212
	v_lshlrev_b32_e32 v216, 16, v212
	v_pk_add_f32 v[26:27], v[26:27], v[216:217]
	v_and_b32_e32 v219, 0xffff0000, v213
	v_lshlrev_b32_e32 v218, 16, v213
	v_pk_add_f32 v[24:25], v[24:25], v[218:219]
	v_and_b32_e32 v217, 0xffff0000, v214
	v_lshlrev_b32_e32 v216, 16, v214
	v_pk_add_f32 v[22:23], v[22:23], v[216:217]
	v_and_b32_e32 v219, 0xffff0000, v215
	v_lshlrev_b32_e32 v218, 16, v215
	v_pk_add_f32 v[20:21], v[20:21], v[218:219]
	s_mov_b64 exec, s[14:15]
	ds_read_b128 v[28:31], v112 offset:7712
	s_mov_b64 s[14:15], 0
	s_waitcnt lgkmcnt(0)
	v_and_b32_e32 v33, 0xffff0000, v28
	v_lshlrev_b32_e32 v32, 16, v28
	v_pk_fma_f32 v[26:27], v[18:19], v[26:27], v[32:33] neg_lo:[0,0,1] neg_hi:[0,0,1]
	v_and_b32_e32 v33, 0xffff0000, v29
	v_lshlrev_b32_e32 v32, 16, v29
	v_pk_fma_f32 v[24:25], v[18:19], v[24:25], v[32:33] neg_lo:[0,0,1] neg_hi:[0,0,1]
	v_cvt_pk_bf16_f32 v26, v26, v27
	v_cvt_pk_bf16_f32 v27, v24, v25
	v_and_b32_e32 v25, 0xffff0000, v30
	v_lshlrev_b32_e32 v24, 16, v30
	v_pk_fma_f32 v[22:23], v[18:19], v[22:23], v[24:25] neg_lo:[0,0,1] neg_hi:[0,0,1]
	s_nop 0
	v_cvt_pk_bf16_f32 v28, v22, v23
	v_and_b32_e32 v23, 0xffff0000, v31
	v_lshlrev_b32_e32 v22, 16, v31
	v_pk_fma_f32 v[20:21], v[18:19], v[20:21], v[22:23] neg_lo:[0,0,1] neg_hi:[0,0,1]
	s_nop 0
	v_cvt_pk_bf16_f32 v29, v20, v21
	v_mov_b32_e32 v20, 0
	ds_write_b128 v113, v[26:29] offset:40480
	v_mov_b32_e32 v28, v105
	v_mov_b32_e32 v29, v0
	v_mov_b32_e32 v21, v20
	v_mov_b32_e32 v26, v20
	v_mov_b32_e32 v27, v20
	v_mov_b32_e32 v24, v20
	v_mov_b32_e32 v25, v20
	v_mov_b32_e32 v22, v20
	v_mov_b32_e32 v23, v20
	s_waitcnt lgkmcnt(0)
	s_mov_b64 s[14:15], exec
	v_add_u32_e32 v220, 0xffffe200, v28
	ds_read_b128 v[136:139], v220 offset:7680
	ds_read_b128 v[140:143], v220 offset:7168
	ds_read_b128 v[144:147], v220 offset:6656
	ds_read_b128 v[148:151], v220 offset:6144
	ds_read_b128 v[152:155], v220 offset:5632
	ds_read_b128 v[156:159], v220 offset:5120
	ds_read_b128 v[160:163], v220 offset:4608
	ds_read_b128 v[164:167], v220 offset:4096
	ds_read_b128 v[184:187], v220 offset:3584
	ds_read_b128 v[188:191], v220 offset:3072
	ds_read_b128 v[192:195], v220 offset:2560
	ds_read_b128 v[196:199], v220 offset:2048
	ds_read_b128 v[200:203], v220 offset:1536
	ds_read_b128 v[204:207], v220 offset:1024
	ds_read_b128 v[208:211], v220 offset:512
	ds_read_b128 v[212:215], v220 offset:0
	v_cmp_lt_u32_e64 s[98:99], 2, v0
	v_cmp_lt_u32_e64 s[100:101], 4, v0
	v_cmp_lt_u32_e64 vcc, 8, v0
	s_waitcnt lgkmcnt(15)
	v_and_b32_e32 v217, 0xffff0000, v136
	v_lshlrev_b32_e32 v216, 16, v136
	v_pk_add_f32 v[26:27], v[26:27], v[216:217]
	v_and_b32_e32 v219, 0xffff0000, v137
	v_lshlrev_b32_e32 v218, 16, v137
	v_pk_add_f32 v[24:25], v[24:25], v[218:219]
	v_and_b32_e32 v217, 0xffff0000, v138
	v_lshlrev_b32_e32 v216, 16, v138
	v_pk_add_f32 v[22:23], v[22:23], v[216:217]
	v_and_b32_e32 v219, 0xffff0000, v139
	v_lshlrev_b32_e32 v218, 16, v139
	v_pk_add_f32 v[20:21], v[20:21], v[218:219]
	s_waitcnt lgkmcnt(14)
	v_and_b32_e32 v217, 0xffff0000, v140
	v_lshlrev_b32_e32 v216, 16, v140
	v_pk_add_f32 v[26:27], v[26:27], v[216:217]
	v_and_b32_e32 v219, 0xffff0000, v141
	v_lshlrev_b32_e32 v218, 16, v141
	v_pk_add_f32 v[24:25], v[24:25], v[218:219]
	v_and_b32_e32 v217, 0xffff0000, v142
	v_lshlrev_b32_e32 v216, 16, v142
	v_pk_add_f32 v[22:23], v[22:23], v[216:217]
	v_and_b32_e32 v219, 0xffff0000, v143
	v_lshlrev_b32_e32 v218, 16, v143
	v_pk_add_f32 v[20:21], v[20:21], v[218:219]
	s_and_b64 exec, s[14:15], s[98:99]
	s_waitcnt lgkmcnt(13)
	v_and_b32_e32 v217, 0xffff0000, v144
	v_lshlrev_b32_e32 v216, 16, v144
	v_pk_add_f32 v[26:27], v[26:27], v[216:217]
	v_and_b32_e32 v219, 0xffff0000, v145
	v_lshlrev_b32_e32 v218, 16, v145
	v_pk_add_f32 v[24:25], v[24:25], v[218:219]
	v_and_b32_e32 v217, 0xffff0000, v146
	v_lshlrev_b32_e32 v216, 16, v146
	v_pk_add_f32 v[22:23], v[22:23], v[216:217]
	v_and_b32_e32 v219, 0xffff0000, v147
	v_lshlrev_b32_e32 v218, 16, v147
	v_pk_add_f32 v[20:21], v[20:21], v[218:219]
	s_waitcnt lgkmcnt(12)
	v_and_b32_e32 v217, 0xffff0000, v148
	v_lshlrev_b32_e32 v216, 16, v148
	v_pk_add_f32 v[26:27], v[26:27], v[216:217]
	v_and_b32_e32 v219, 0xffff0000, v149
	v_lshlrev_b32_e32 v218, 16, v149
	v_pk_add_f32 v[24:25], v[24:25], v[218:219]
	v_and_b32_e32 v217, 0xffff0000, v150
	v_lshlrev_b32_e32 v216, 16, v150
	v_pk_add_f32 v[22:23], v[22:23], v[216:217]
	v_and_b32_e32 v219, 0xffff0000, v151
	v_lshlrev_b32_e32 v218, 16, v151
	v_pk_add_f32 v[20:21], v[20:21], v[218:219]
	s_and_b64 exec, s[14:15], s[100:101]
	s_waitcnt lgkmcnt(11)
	v_and_b32_e32 v217, 0xffff0000, v152
	v_lshlrev_b32_e32 v216, 16, v152
	v_pk_add_f32 v[26:27], v[26:27], v[216:217]
	v_and_b32_e32 v219, 0xffff0000, v153
	v_lshlrev_b32_e32 v218, 16, v153
	v_pk_add_f32 v[24:25], v[24:25], v[218:219]
	v_and_b32_e32 v217, 0xffff0000, v154
	v_lshlrev_b32_e32 v216, 16, v154
	v_pk_add_f32 v[22:23], v[22:23], v[216:217]
	v_and_b32_e32 v219, 0xffff0000, v155
	v_lshlrev_b32_e32 v218, 16, v155
	v_pk_add_f32 v[20:21], v[20:21], v[218:219]
	s_waitcnt lgkmcnt(10)
	v_and_b32_e32 v217, 0xffff0000, v156
	v_lshlrev_b32_e32 v216, 16, v156
	v_pk_add_f32 v[26:27], v[26:27], v[216:217]
	v_and_b32_e32 v219, 0xffff0000, v157
	v_lshlrev_b32_e32 v218, 16, v157
	v_pk_add_f32 v[24:25], v[24:25], v[218:219]
	v_and_b32_e32 v217, 0xffff0000, v158
	v_lshlrev_b32_e32 v216, 16, v158
	v_pk_add_f32 v[22:23], v[22:23], v[216:217]
	v_and_b32_e32 v219, 0xffff0000, v159
	v_lshlrev_b32_e32 v218, 16, v159
	v_pk_add_f32 v[20:21], v[20:21], v[218:219]
	s_waitcnt lgkmcnt(9)
	v_and_b32_e32 v217, 0xffff0000, v160
	v_lshlrev_b32_e32 v216, 16, v160
	v_pk_add_f32 v[26:27], v[26:27], v[216:217]
	v_and_b32_e32 v219, 0xffff0000, v161
	v_lshlrev_b32_e32 v218, 16, v161
	v_pk_add_f32 v[24:25], v[24:25], v[218:219]
	v_and_b32_e32 v217, 0xffff0000, v162
	v_lshlrev_b32_e32 v216, 16, v162
	v_pk_add_f32 v[22:23], v[22:23], v[216:217]
	v_and_b32_e32 v219, 0xffff0000, v163
	v_lshlrev_b32_e32 v218, 16, v163
	v_pk_add_f32 v[20:21], v[20:21], v[218:219]
	s_waitcnt lgkmcnt(8)
	v_and_b32_e32 v217, 0xffff0000, v164
	v_lshlrev_b32_e32 v216, 16, v164
	v_pk_add_f32 v[26:27], v[26:27], v[216:217]
	v_and_b32_e32 v219, 0xffff0000, v165
	v_lshlrev_b32_e32 v218, 16, v165
	v_pk_add_f32 v[24:25], v[24:25], v[218:219]
	v_and_b32_e32 v217, 0xffff0000, v166
	v_lshlrev_b32_e32 v216, 16, v166
	v_pk_add_f32 v[22:23], v[22:23], v[216:217]
	v_and_b32_e32 v219, 0xffff0000, v167
	v_lshlrev_b32_e32 v218, 16, v167
	v_pk_add_f32 v[20:21], v[20:21], v[218:219]
	s_and_b64 exec, s[14:15], vcc
	s_waitcnt lgkmcnt(7)
	v_and_b32_e32 v217, 0xffff0000, v184
	v_lshlrev_b32_e32 v216, 16, v184
	v_pk_add_f32 v[26:27], v[26:27], v[216:217]
	v_and_b32_e32 v219, 0xffff0000, v185
	v_lshlrev_b32_e32 v218, 16, v185
	v_pk_add_f32 v[24:25], v[24:25], v[218:219]
	v_and_b32_e32 v217, 0xffff0000, v186
	v_lshlrev_b32_e32 v216, 16, v186
	v_pk_add_f32 v[22:23], v[22:23], v[216:217]
	v_and_b32_e32 v219, 0xffff0000, v187
	v_lshlrev_b32_e32 v218, 16, v187
	v_pk_add_f32 v[20:21], v[20:21], v[218:219]
	s_waitcnt lgkmcnt(6)
	v_and_b32_e32 v217, 0xffff0000, v188
	v_lshlrev_b32_e32 v216, 16, v188
	v_pk_add_f32 v[26:27], v[26:27], v[216:217]
	v_and_b32_e32 v219, 0xffff0000, v189
	v_lshlrev_b32_e32 v218, 16, v189
	v_pk_add_f32 v[24:25], v[24:25], v[218:219]
	v_and_b32_e32 v217, 0xffff0000, v190
	v_lshlrev_b32_e32 v216, 16, v190
	v_pk_add_f32 v[22:23], v[22:23], v[216:217]
	v_and_b32_e32 v219, 0xffff0000, v191
	v_lshlrev_b32_e32 v218, 16, v191
	v_pk_add_f32 v[20:21], v[20:21], v[218:219]
	s_waitcnt lgkmcnt(5)
	v_and_b32_e32 v217, 0xffff0000, v192
	v_lshlrev_b32_e32 v216, 16, v192
	v_pk_add_f32 v[26:27], v[26:27], v[216:217]
	v_and_b32_e32 v219, 0xffff0000, v193
	v_lshlrev_b32_e32 v218, 16, v193
	v_pk_add_f32 v[24:25], v[24:25], v[218:219]
	v_and_b32_e32 v217, 0xffff0000, v194
	v_lshlrev_b32_e32 v216, 16, v194
	v_pk_add_f32 v[22:23], v[22:23], v[216:217]
	v_and_b32_e32 v219, 0xffff0000, v195
	v_lshlrev_b32_e32 v218, 16, v195
	v_pk_add_f32 v[20:21], v[20:21], v[218:219]
	s_waitcnt lgkmcnt(4)
	v_and_b32_e32 v217, 0xffff0000, v196
	v_lshlrev_b32_e32 v216, 16, v196
	v_pk_add_f32 v[26:27], v[26:27], v[216:217]
	v_and_b32_e32 v219, 0xffff0000, v197
	v_lshlrev_b32_e32 v218, 16, v197
	v_pk_add_f32 v[24:25], v[24:25], v[218:219]
	v_and_b32_e32 v217, 0xffff0000, v198
	v_lshlrev_b32_e32 v216, 16, v198
	v_pk_add_f32 v[22:23], v[22:23], v[216:217]
	v_and_b32_e32 v219, 0xffff0000, v199
	v_lshlrev_b32_e32 v218, 16, v199
	v_pk_add_f32 v[20:21], v[20:21], v[218:219]
	s_waitcnt lgkmcnt(3)
	v_and_b32_e32 v217, 0xffff0000, v200
	v_lshlrev_b32_e32 v216, 16, v200
	v_pk_add_f32 v[26:27], v[26:27], v[216:217]
	v_and_b32_e32 v219, 0xffff0000, v201
	v_lshlrev_b32_e32 v218, 16, v201
	v_pk_add_f32 v[24:25], v[24:25], v[218:219]
	v_and_b32_e32 v217, 0xffff0000, v202
	v_lshlrev_b32_e32 v216, 16, v202
	v_pk_add_f32 v[22:23], v[22:23], v[216:217]
	v_and_b32_e32 v219, 0xffff0000, v203
	v_lshlrev_b32_e32 v218, 16, v203
	v_pk_add_f32 v[20:21], v[20:21], v[218:219]
	s_waitcnt lgkmcnt(2)
	v_and_b32_e32 v217, 0xffff0000, v204
	v_lshlrev_b32_e32 v216, 16, v204
	v_pk_add_f32 v[26:27], v[26:27], v[216:217]
	v_and_b32_e32 v219, 0xffff0000, v205
	v_lshlrev_b32_e32 v218, 16, v205
	v_pk_add_f32 v[24:25], v[24:25], v[218:219]
	v_and_b32_e32 v217, 0xffff0000, v206
	v_lshlrev_b32_e32 v216, 16, v206
	v_pk_add_f32 v[22:23], v[22:23], v[216:217]
	v_and_b32_e32 v219, 0xffff0000, v207
	v_lshlrev_b32_e32 v218, 16, v207
	v_pk_add_f32 v[20:21], v[20:21], v[218:219]
	s_waitcnt lgkmcnt(1)
	v_and_b32_e32 v217, 0xffff0000, v208
	v_lshlrev_b32_e32 v216, 16, v208
	v_pk_add_f32 v[26:27], v[26:27], v[216:217]
	v_and_b32_e32 v219, 0xffff0000, v209
	v_lshlrev_b32_e32 v218, 16, v209
	v_pk_add_f32 v[24:25], v[24:25], v[218:219]
	v_and_b32_e32 v217, 0xffff0000, v210
	v_lshlrev_b32_e32 v216, 16, v210
	v_pk_add_f32 v[22:23], v[22:23], v[216:217]
	v_and_b32_e32 v219, 0xffff0000, v211
	v_lshlrev_b32_e32 v218, 16, v211
	v_pk_add_f32 v[20:21], v[20:21], v[218:219]
	s_waitcnt lgkmcnt(0)
	v_and_b32_e32 v217, 0xffff0000, v212
	v_lshlrev_b32_e32 v216, 16, v212
	v_pk_add_f32 v[26:27], v[26:27], v[216:217]
	v_and_b32_e32 v219, 0xffff0000, v213
	v_lshlrev_b32_e32 v218, 16, v213
	v_pk_add_f32 v[24:25], v[24:25], v[218:219]
	v_and_b32_e32 v217, 0xffff0000, v214
	v_lshlrev_b32_e32 v216, 16, v214
	v_pk_add_f32 v[22:23], v[22:23], v[216:217]
	v_and_b32_e32 v219, 0xffff0000, v215
	v_lshlrev_b32_e32 v218, 16, v215
	v_pk_add_f32 v[20:21], v[20:21], v[218:219]
	s_mov_b64 exec, s[14:15]
	ds_read_b128 v[28:31], v112 offset:7728
	s_cmp_eq_u32 s3, s80
	s_waitcnt lgkmcnt(0)
	v_and_b32_e32 v33, 0xffff0000, v28
	v_lshlrev_b32_e32 v32, 16, v28
	v_pk_fma_f32 v[26:27], v[18:19], v[26:27], v[32:33] neg_lo:[0,0,1] neg_hi:[0,0,1]
	v_and_b32_e32 v33, 0xffff0000, v29
	v_lshlrev_b32_e32 v32, 16, v29
	v_pk_fma_f32 v[24:25], v[18:19], v[24:25], v[32:33] neg_lo:[0,0,1] neg_hi:[0,0,1]
	v_cvt_pk_bf16_f32 v26, v26, v27
	v_cvt_pk_bf16_f32 v27, v24, v25
	v_and_b32_e32 v25, 0xffff0000, v30
	v_lshlrev_b32_e32 v24, 16, v30
	v_pk_fma_f32 v[22:23], v[18:19], v[22:23], v[24:25] neg_lo:[0,0,1] neg_hi:[0,0,1]
	s_nop 0
	v_cvt_pk_bf16_f32 v28, v22, v23
	v_and_b32_e32 v23, 0xffff0000, v31
	v_lshlrev_b32_e32 v22, 16, v31
	v_pk_fma_f32 v[18:19], v[18:19], v[20:21], v[22:23] neg_lo:[0,0,1] neg_hi:[0,0,1]
	s_nop 0
	v_cvt_pk_bf16_f32 v29, v18, v19
	ds_write_b128 v113, v[26:29] offset:40496
	s_waitcnt lgkmcnt(0)
	s_barrier
	ds_read_b128 v[18:21], v111 offset:40448
	ds_read_b128 v[114:117], v111 offset:40480
	s_waitcnt vmcnt(9) lgkmcnt(1)
	v_mfma_f32_32x32x16_bf16 v[34:49], v[18:21], v[50:53], 0
	s_waitcnt vmcnt(8)
	v_mfma_f32_32x32x16_bf16 v[18:33], v[18:21], v[54:57], 0
	s_waitcnt vmcnt(7) lgkmcnt(0)
	v_mfma_f32_32x32x16_bf16 v[34:49], v[114:117], v[58:61], v[34:49]
	s_waitcnt vmcnt(6)
	v_mfma_f32_32x32x16_bf16 v[18:33], v[114:117], v[62:65], v[18:33]
	ds_read_b128 v[114:117], v111 offset:40512
	s_waitcnt vmcnt(5) lgkmcnt(0)
	v_mfma_f32_32x32x16_bf16 v[34:49], v[114:117], v[66:69], v[34:49]
	s_waitcnt vmcnt(4)
	v_mfma_f32_32x32x16_bf16 v[18:33], v[114:117], v[70:73], v[18:33]
	ds_read_b128 v[114:117], v111 offset:40544
	s_waitcnt vmcnt(3) lgkmcnt(0)
	v_mfma_f32_32x32x16_bf16 v[34:49], v[114:117], v[78:81], v[34:49]
	s_waitcnt vmcnt(2)
	v_mfma_f32_32x32x16_bf16 v[18:33], v[114:117], v[82:85], v[18:33]
	v_or_b32_e32 v114, s16, v101
	v_ashrrev_i32_e32 v115, 31, v114
	s_waitcnt vmcnt(1)
	s_nop 6
	v_mul_f32_e32 v34, v98, v34
	v_lshlrev_b64 v[116:117], 11, v[114:115]
	v_cvt_pk_bf16_f32 v34, v34, s0
	v_lshl_add_u64 v[118:119], v[90:91], 0, v[116:117]
	global_store_short v[118:119], v34, off
	v_or_b32_e32 v34, 1, v114
	v_mul_f32_e32 v35, v98, v35
	v_cvt_pk_bf16_f32 v115, v35, s0
	v_ashrrev_i32_e32 v35, 31, v34
	v_lshlrev_b64 v[34:35], 11, v[34:35]
	v_lshl_add_u64 v[118:119], v[90:91], 0, v[34:35]
	global_store_short v[118:119], v115, off
	v_or_b32_e32 v118, 2, v114
	v_ashrrev_i32_e32 v119, 31, v118
	v_mul_f32_e32 v36, v98, v36
	v_lshlrev_b64 v[118:119], 11, v[118:119]
	v_cvt_pk_bf16_f32 v36, v36, s0
	v_lshl_add_u64 v[120:121], v[90:91], 0, v[118:119]
	global_store_short v[120:121], v36, off
	v_or_b32_e32 v36, 3, v114
	v_mul_f32_e32 v37, v98, v37
	v_cvt_pk_bf16_f32 v115, v37, s0
	v_ashrrev_i32_e32 v37, 31, v36
	v_lshlrev_b64 v[36:37], 11, v[36:37]
	v_lshl_add_u64 v[120:121], v[90:91], 0, v[36:37]
	global_store_short v[120:121], v115, off
	v_or_b32_e32 v120, 8, v114
	v_ashrrev_i32_e32 v121, 31, v120
	v_mul_f32_e32 v38, v98, v38
	v_lshlrev_b64 v[120:121], 11, v[120:121]
	v_cvt_pk_bf16_f32 v38, v38, s0
	v_lshl_add_u64 v[122:123], v[90:91], 0, v[120:121]
	global_store_short v[122:123], v38, off
	v_or_b32_e32 v38, 9, v114
	v_mul_f32_e32 v39, v98, v39
	v_cvt_pk_bf16_f32 v115, v39, s0
	v_ashrrev_i32_e32 v39, 31, v38
	v_lshlrev_b64 v[38:39], 11, v[38:39]
	v_lshl_add_u64 v[122:123], v[90:91], 0, v[38:39]
	global_store_short v[122:123], v115, off
	v_or_b32_e32 v122, 10, v114
	v_ashrrev_i32_e32 v123, 31, v122
	v_mul_f32_e32 v40, v98, v40
	v_lshlrev_b64 v[122:123], 11, v[122:123]
	v_cvt_pk_bf16_f32 v40, v40, s0
	v_lshl_add_u64 v[124:125], v[90:91], 0, v[122:123]
	global_store_short v[124:125], v40, off
	v_or_b32_e32 v40, 11, v114
	v_mul_f32_e32 v41, v98, v41
	v_cvt_pk_bf16_f32 v115, v41, s0
	v_ashrrev_i32_e32 v41, 31, v40
	v_lshlrev_b64 v[40:41], 11, v[40:41]
	v_lshl_add_u64 v[124:125], v[90:91], 0, v[40:41]
	global_store_short v[124:125], v115, off
	v_or_b32_e32 v124, 16, v114
	v_ashrrev_i32_e32 v125, 31, v124
	v_mul_f32_e32 v42, v98, v42
	v_lshlrev_b64 v[124:125], 11, v[124:125]
	v_cvt_pk_bf16_f32 v42, v42, s0
	v_lshl_add_u64 v[126:127], v[90:91], 0, v[124:125]
	global_store_short v[126:127], v42, off
	v_or_b32_e32 v42, 17, v114
	v_mul_f32_e32 v43, v98, v43
	v_cvt_pk_bf16_f32 v115, v43, s0
	v_ashrrev_i32_e32 v43, 31, v42
	v_lshlrev_b64 v[42:43], 11, v[42:43]
	v_lshl_add_u64 v[126:127], v[90:91], 0, v[42:43]
	global_store_short v[126:127], v115, off
	v_or_b32_e32 v126, 18, v114
	v_ashrrev_i32_e32 v127, 31, v126
	v_mul_f32_e32 v44, v98, v44
	v_lshlrev_b64 v[126:127], 11, v[126:127]
	v_cvt_pk_bf16_f32 v44, v44, s0
	v_lshl_add_u64 v[128:129], v[90:91], 0, v[126:127]
	global_store_short v[128:129], v44, off
	v_or_b32_e32 v44, 19, v114
	v_mul_f32_e32 v45, v98, v45
	v_cvt_pk_bf16_f32 v115, v45, s0
	v_ashrrev_i32_e32 v45, 31, v44
	v_lshlrev_b64 v[44:45], 11, v[44:45]
	v_lshl_add_u64 v[128:129], v[90:91], 0, v[44:45]
	global_store_short v[128:129], v115, off
	v_or_b32_e32 v128, 24, v114
	v_ashrrev_i32_e32 v129, 31, v128
	v_mul_f32_e32 v46, v98, v46
	v_lshlrev_b64 v[128:129], 11, v[128:129]
	v_cvt_pk_bf16_f32 v46, v46, s0
	v_lshl_add_u64 v[130:131], v[90:91], 0, v[128:129]
	global_store_short v[130:131], v46, off
	v_or_b32_e32 v46, 25, v114
	v_mul_f32_e32 v47, v98, v47
	v_cvt_pk_bf16_f32 v115, v47, s0
	v_ashrrev_i32_e32 v47, 31, v46
	v_lshlrev_b64 v[46:47], 11, v[46:47]
	v_lshl_add_u64 v[130:131], v[90:91], 0, v[46:47]
	global_store_short v[130:131], v115, off
	v_or_b32_e32 v130, 26, v114
	v_ashrrev_i32_e32 v131, 31, v130
	v_mul_f32_e32 v48, v98, v48
	v_lshlrev_b64 v[130:131], 11, v[130:131]
	v_cvt_pk_bf16_f32 v48, v48, s0
	v_lshl_add_u64 v[132:133], v[90:91], 0, v[130:131]
	global_store_short v[132:133], v48, off
	v_or_b32_e32 v48, 27, v114
	v_mul_f32_e32 v49, v98, v49
	v_cvt_pk_bf16_f32 v132, v49, s0
	v_ashrrev_i32_e32 v49, 31, v48
	v_lshlrev_b64 v[48:49], 11, v[48:49]
	v_lshl_add_u64 v[114:115], v[90:91], 0, v[48:49]
	s_waitcnt vmcnt(15)
	v_mul_f32_e32 v18, v99, v18
	global_store_short v[114:115], v132, off
	v_cvt_pk_bf16_f32 v18, v18, s0
	v_lshl_add_u64 v[114:115], v[92:93], 0, v[116:117]
	global_store_short v[114:115], v18, off
	v_mul_f32_e32 v18, v99, v19
	v_cvt_pk_bf16_f32 v114, v18, s0
	v_lshl_add_u64 v[18:19], v[92:93], 0, v[34:35]
	global_store_short v[18:19], v114, off
	v_mul_f32_e32 v18, v99, v20
	v_cvt_pk_bf16_f32 v20, v18, s0
	v_lshl_add_u64 v[18:19], v[92:93], 0, v[118:119]
	global_store_short v[18:19], v20, off
	v_mul_f32_e32 v18, v99, v21
	v_cvt_pk_bf16_f32 v20, v18, s0
	v_lshl_add_u64 v[18:19], v[92:93], 0, v[36:37]
	global_store_short v[18:19], v20, off
	v_mul_f32_e32 v18, v99, v22
	v_cvt_pk_bf16_f32 v20, v18, s0
	v_lshl_add_u64 v[18:19], v[92:93], 0, v[120:121]
	global_store_short v[18:19], v20, off
	v_mul_f32_e32 v18, v99, v23
	v_cvt_pk_bf16_f32 v20, v18, s0
	v_lshl_add_u64 v[18:19], v[92:93], 0, v[38:39]
	global_store_short v[18:19], v20, off
	v_mul_f32_e32 v18, v99, v24
	v_cvt_pk_bf16_f32 v20, v18, s0
	v_lshl_add_u64 v[18:19], v[92:93], 0, v[122:123]
	global_store_short v[18:19], v20, off
	v_mul_f32_e32 v18, v99, v25
	v_cvt_pk_bf16_f32 v20, v18, s0
	v_lshl_add_u64 v[18:19], v[92:93], 0, v[40:41]
	global_store_short v[18:19], v20, off
	v_mul_f32_e32 v18, v99, v26
	v_cvt_pk_bf16_f32 v20, v18, s0
	v_lshl_add_u64 v[18:19], v[92:93], 0, v[124:125]
	global_store_short v[18:19], v20, off
	v_mul_f32_e32 v18, v99, v27
	v_cvt_pk_bf16_f32 v20, v18, s0
	v_lshl_add_u64 v[18:19], v[92:93], 0, v[42:43]
	global_store_short v[18:19], v20, off
	v_mul_f32_e32 v18, v99, v28
	v_cvt_pk_bf16_f32 v20, v18, s0
	v_lshl_add_u64 v[18:19], v[92:93], 0, v[126:127]
	global_store_short v[18:19], v20, off
	v_mul_f32_e32 v18, v99, v29
	v_cvt_pk_bf16_f32 v20, v18, s0
	v_lshl_add_u64 v[18:19], v[92:93], 0, v[44:45]
	global_store_short v[18:19], v20, off
	v_mul_f32_e32 v18, v99, v30
	v_cvt_pk_bf16_f32 v20, v18, s0
	v_lshl_add_u64 v[18:19], v[92:93], 0, v[128:129]
	global_store_short v[18:19], v20, off
	v_mul_f32_e32 v18, v99, v31
	v_cvt_pk_bf16_f32 v20, v18, s0
	v_lshl_add_u64 v[18:19], v[92:93], 0, v[46:47]
	global_store_short v[18:19], v20, off
	v_mul_f32_e32 v18, v99, v32
	v_cvt_pk_bf16_f32 v20, v18, s0
	v_lshl_add_u64 v[18:19], v[92:93], 0, v[130:131]
	global_store_short v[18:19], v20, off
	v_mul_f32_e32 v18, v99, v33
	v_cvt_pk_bf16_f32 v20, v18, s0
	v_lshl_add_u64 v[18:19], v[92:93], 0, v[48:49]
	global_store_short v[18:19], v20, off
	s_barrier
	s_cbranch_scc0 .LBB0_701
	s_branch .LBB0_722
